# scan: loader waves' per-lane staging / request addresses hoisted out of the chunk loop (saddr-form loads), chain wave block re-scheduled; on top of nt hints + interleaved dequant scales + s_sleep 8
# speedup vs baseline: 1.0039x; 1.0039x over previous
; #define GAS __attribute__((address_space(1)))
; #define LAS __attribute__((address_space(3)))
; __device__ __forceinline__ void phase_hgrn_scan(LAS unsigned char* lds, unsigned char* ws, const float* scratch) {
;     ...
;         auto load_chunk = [&](int n) {
;             int lane = lane0; asm volatile("" : "+v"(lane));
;             const size_t gch = (size_t)b * 128 + n, t0 = gch * 32;
;             if (lw >= 0 && lw < 4) { const bf16* src = ((lw < 2) ? KI : QI) + (t0 + (lw & 1) * 16 + (lane >> 4)) * D + h * 128 + 8 * (lane & 15);
; #pragma unroll
;                 for (int i = 0; i < 4; ++i) rg[i] = *(const GAS v4u*)(src + (size_t)(4 * i) * D);
;                 if (lw == 1 && lane < 32) rg[4] = *(const GAS v4u*)(DEC + gch * 1024 + h * 128 + 4 * lane);
;             } else if (lw >= 4) { const bf16* src = KOT + (gch * 1024 + h * 128 + (lw - 4) * 64 + (lane >> 2)) * 32 + 8 * (lane & 3);
; #pragma unroll
;                 for (int i = 0; i < 4; ++i) rg[i] = *(const GAS v4u*)(src + (size_t)(16 * i) * 32);
;                 rg[4] = *(const GAS v4u*)(CV + (t0 + (lw - 4) * 16 + (lane >> 2)) * D + h * 128 + es * 32 + 8 * (lane & 3));
;             }
;         };
;         auto store_chunk = [&](int bufi) {
;             int lane = lane0; asm volatile("" : "+v"(lane));
;             LAS unsigned char* bp = lds + bufi * BUF;
;             if (lw >= 0 && lw < 4) { LAS unsigned char* dst = bp + ((lw < 2) ? O_KI : O_QI) + ((lw & 1) * 16 + (lane >> 4)) * 272 + (lane & 15) * 16;
; #pragma unroll
;                 for (int i = 0; i < 4; ++i) *(LAS v4u*)(dst + (4 * i) * 272) = rg[i];
;                 if (lw == 1 && lane < 32) *(LAS v4u*)(bp + O_DEC + 16 * lane) = rg[4];
;             } else if (lw >= 4) { LAS unsigned char* dst = bp + O_KOT + ((lw - 4) * 64 + (lane >> 2)) * 80 + (lane & 3) * 16;
; #pragma unroll
;                 for (int i = 0; i < 4; ++i) *(LAS v4u*)(dst + (16 * i) * 80) = rg[i];
;                 *(LAS v4u*)(bp + O_VT + ((lw - 4) * 16 + (lane >> 2)) * 64 + (lane & 3) * 16) = rg[4];
;             }
;         };
;     ...
;         for (int n = 0; n < 128; ++n) {
;             if (n + 2 < 128) store_chunk((n + 2) % 3);
;             if (n + 3 < 128) load_chunk(n + 3);
;             if (wave == 1 && n + 1 < 128) scores(n + 1);
.LBB0_1301:
	s_lshr_b32 s0, s59, 3
	s_and_b32 s0, s0, 3
	s_lshl_b32 s62, s62, 5
	s_lshl_b32 s56, s0, 6
	s_lshl_b64 s[54:55], s[88:89], 23
	s_lshl_b64 s[0:1], s[88:89], 17
	s_add_u32 s0, s0, s49
	s_addc_u32 s1, s1, 0
	s_add_u32 s0, s0, 0x1000
	s_addc_u32 s1, s1, 0
	s_lshl_b32 s49, s59, 4
	s_lshl_b64 s[2:3], s[88:89], 19
	s_and_b32 s49, s49, 0xe00
	s_or_b32 s2, s2, s49
	s_add_u32 s52, s2, 0x1e004000
	s_addc_u32 s63, s3, 0
	v_readlane_b32 s2, v255, 43
	s_add_u32 s88, s2, s44
	s_addc_u32 s89, 0, s45
	v_readlane_b32 s2, v255, 44
	s_add_u32 s90, s2, s44
	v_readlane_b32 s2, v255, 45
	s_addc_u32 s91, s2, s45
	s_and_b32 s2, s61, 0x700
	s_or_b32 s2, s56, s2
	s_or_b32 s2, s54, s2
	s_mov_b32 s3, s55
	v_lshl_add_u64 v[136:137], s[2:3], 0, v[132:133]
	s_mov_b32 s61, 0
	s_mov_b32 s49, 0
	s_waitcnt lgkmcnt(0)
	s_and_b64 vcc, exec, s[78:79]
	s_cbranch_vccnz .Lscan_pre_kot
	v_lshrrev_b32_e32 v246, 4, v1
	v_add_u32_e32 v246, s96, v246
	v_mul_lo_u32 v246, v246, s33
	v_lshlrev_b32_e32 v252, 4, v1
	v_and_b32_e32 v247, 0xf0, v252
	v_add3_u32 v246, s67, v246, v247
	v_lshrrev_b32_e32 v248, 4, v1
	v_lshl_or_b32 v248, v248, 11, v247
	v_add_u32_e32 v249, 0x2000, v248
	v_add_u32_e32 v250, 0x4000, v248
	v_add_u32_e32 v251, 0x6000, v248
	v_mov_b32_e32 v253, 0
	s_branch .Lscan_pre_done
.Lscan_pre_kot:
	v_lshrrev_b32_e32 v246, 2, v1
	v_add_u32_e32 v247, s51, v246
	v_mul_lo_u32 v247, v247, s50
	v_lshlrev_b32_e32 v248, 4, v1
	v_and_b32_e32 v249, 48, v248
	v_lshl_add_u32 v250, v246, 6, v249
	v_lshl_or_b32 v252, v246, 11, v249
	v_add_u32_e32 v246, v247, v249
	v_add_u32_e32 v247, s66, v250
	v_mov_b32_e32 v253, 0
.Lscan_pre_done:
	s_barrier
.LBB0_1302:
	s_add_i32 s2, s49, 3
	s_and_b32 s3, s2, 0xff
	s_mulk_i32 s3, 0xab
	s_bfe_u32 s3, s3, 0x70009
	s_mul_i32 s3, s3, 3
	s_sub_i32 s2, s2, s3
	s_and_b32 s2, s2, 0xff
	s_mulk_i32 s2, 0x7800
	v_mov_b32_e32 v2, v1
	s_add_i32 s58, s2, 0
	s_mov_b64 s[2:3], -1
	s_and_b64 vcc, exec, s[76:77]
	s_cbranch_vccnz .LBB0_1311
	s_andn2_b64 vcc, exec, s[2:3]
	s_cbranch_vccz .LBB0_1314

; #define LAS __attribute__((address_space(3)))
; __device__ __forceinline__ void phase_hgrn_scan(LAS unsigned char* lds, unsigned char* ws, const float* scratch) {
;     ...
;             } else if (lw >= 4) { LAS unsigned char* dst = bp + O_KOT + ((lw - 4) * 64 + (lane >> 2)) * 80 + (lane & 3) * 16;
; #pragma unroll
;                 for (int i = 0; i < 4; ++i) *(LAS v4u*)(dst + (16 * i) * 80) = rg[i];
;                 *(LAS v4u*)(bp + O_VT + ((lw - 4) * 16 + (lane >> 2)) * 64 + (lane & 3) * 16) = rg[4];
.LBB0_1311:
	s_and_b64 vcc, exec, s[38:39]
	s_cbranch_vccnz .LBB0_1313
	v_add_u32_e32 v69, s58, v246
	v_add_u32_e32 v68, s58, v247
	s_waitcnt vmcnt(3)
	ds_write_b128 v69, v[104:107] offset:17408
	s_waitcnt vmcnt(2)
	ds_write_b128 v69, v[108:111] offset:18688
	s_waitcnt vmcnt(1)
	ds_write_b128 v69, v[112:115] offset:19968
	s_waitcnt vmcnt(0)
	ds_write_b128 v69, v[116:119] offset:21248
	ds_write_b128 v68, v[100:103] offset:23552

; #define LAS __attribute__((address_space(3)))
; __device__ __forceinline__ void phase_hgrn_scan(LAS unsigned char* lds, unsigned char* ws, const float* scratch) {
;     ...
;             if (lw >= 0 && lw < 4) { LAS unsigned char* dst = bp + ((lw < 2) ? O_KI : O_QI) + ((lw & 1) * 16 + (lane >> 4)) * 272 + (lane & 15) * 16;
; #pragma unroll
;                 for (int i = 0; i < 4; ++i) *(LAS v4u*)(dst + (4 * i) * 272) = rg[i];
;                 if (lw == 1 && lane < 32) *(LAS v4u*)(bp + O_DEC + 16 * lane) = rg[4];
.LBB0_1314:
	v_add_u32_e32 v69, s58, v246
	v_cmp_gt_i32_e32 vcc, 32, v2
	s_and_b64 s[44:45], s[92:93], vcc
	s_waitcnt vmcnt(3)
	ds_write_b128 v69, v[104:107]
	s_waitcnt vmcnt(2)
	ds_write_b128 v69, v[108:111] offset:1088
	s_waitcnt vmcnt(1)
	ds_write_b128 v69, v[112:115] offset:2176
	s_waitcnt vmcnt(0)
	ds_write_b128 v69, v[116:119] offset:3264
	s_and_saveexec_b64 s[2:3], s[44:45]
	v_add_u32_e32 v2, s58, v252
	ds_write_b128 v2, v[100:103] offset:30208
	s_or_b64 exec, exec, s[2:3]
	s_add_i32 s56, s49, 1
	s_cmpk_gt_u32 s56, 0x7c
	s_cbranch_scc1 .LBB0_1305

; #define GAS __attribute__((address_space(1)))
; __device__ __forceinline__ void phase_hgrn_scan(LAS unsigned char* lds, unsigned char* ws, const float* scratch) {
;     ...
;         auto load_chunk = [&](int n) {
;             int lane = lane0; asm volatile("" : "+v"(lane));
;             const size_t gch = (size_t)b * 128 + n, t0 = gch * 32;
;             if (lw >= 0 && lw < 4) { const bf16* src = ((lw < 2) ? KI : QI) + (t0 + (lw & 1) * 16 + (lane >> 4)) * D + h * 128 + 8 * (lane & 15);
; #pragma unroll
;                 for (int i = 0; i < 4; ++i) rg[i] = *(const GAS v4u*)(src + (size_t)(4 * i) * D);
;                 if (lw == 1 && lane < 32) rg[4] = *(const GAS v4u*)(DEC + gch * 1024 + h * 128 + 4 * lane);
;             } else if (lw >= 4) { const bf16* src = KOT + (gch * 1024 + h * 128 + (lw - 4) * 64 + (lane >> 2)) * 32 + 8 * (lane & 3);
; #pragma unroll
;                 for (int i = 0; i < 4; ++i) rg[i] = *(const GAS v4u*)(src + (size_t)(16 * i) * 32);
;                 rg[4] = *(const GAS v4u*)(CV + (t0 + (lw - 4) * 16 + (lane >> 2)) * D + h * 128 + es * 32 + 8 * (lane & 3));
;             }
.LBB0_1326:
	s_lshl_b64 s[100:101], s[0:1], 6
	s_add_u32 s100, s100, s80
	s_addc_u32 s101, s101, s81
	global_load_dwordx4 v[104:107], v248, s[100:101]
	global_load_dwordx4 v[108:111], v248, s[100:101] offset:1024
	global_load_dwordx4 v[112:115], v248, s[100:101] offset:2048
	global_load_dwordx4 v[116:119], v248, s[100:101] offset:3072
	s_lshl_b64 s[98:99], s[90:91], 11
	s_add_u32 s98, s98, s68
	s_addc_u32 s99, s99, s69
	v_lshl_add_u64 v[68:69], s[98:99], 0, v[252:253]
	s_mov_b64 s[44:45], -1
	s_and_b64 vcc, exec, s[2:3]
	s_cbranch_vccz .LBB0_1320
.LBB0_1327:
	s_lshl_b64 s[100:101], s[88:89], 11
	s_add_u32 s100, s100, s70
	s_addc_u32 s101, s101, s71
	global_load_dwordx4 v[104:107], v248, s[100:101]
	global_load_dwordx4 v[108:111], v249, s[100:101]
	global_load_dwordx4 v[112:115], v250, s[100:101]
	global_load_dwordx4 v[116:119], v251, s[100:101]
	v_cmp_gt_i32_e32 vcc, 32, v70
	s_and_b64 vcc, s[92:93], vcc
	s_and_saveexec_b64 s[2:3], vcc
	s_add_u32 s98, s82, s52
	s_addc_u32 s99, s83, s63
	v_lshl_add_u64 v[68:69], s[98:99], 0, v[252:253]
	s_or_b64 s[44:45], s[44:45], exec
	s_or_b64 exec, exec, s[2:3]
	s_and_saveexec_b64 s[2:3], s[44:45]
	s_cbranch_execnz .LBB0_1321
	s_branch .LBB0_1322

; __global__ void __launch_bounds__(NTHR, 2) mk_fwd(Args args) {
	.amdhsa_kernel _Z6mk_fwd4Args
		.amdhsa_group_segment_fixed_size 0
		.amdhsa_private_segment_fixed_size 0
		.amdhsa_kernarg_size 416
		.amdhsa_user_sgpr_count 2
		.amdhsa_user_sgpr_dispatch_ptr 0
		.amdhsa_user_sgpr_queue_ptr 0
		.amdhsa_user_sgpr_kernarg_segment_ptr 1
		.amdhsa_user_sgpr_dispatch_id 0
		.amdhsa_user_sgpr_kernarg_preload_length 0
		.amdhsa_user_sgpr_kernarg_preload_offset 0
		.amdhsa_user_sgpr_private_segment_size 0
		.amdhsa_uses_dynamic_stack 0
		.amdhsa_enable_private_segment 0
		.amdhsa_system_sgpr_workgroup_id_x 1
		.amdhsa_system_sgpr_workgroup_id_y 0
		.amdhsa_system_sgpr_workgroup_id_z 0
		.amdhsa_system_sgpr_workgroup_info 0
		.amdhsa_system_vgpr_workitem_id 0
		.amdhsa_next_free_vgpr 256
		.amdhsa_next_free_sgpr 102
		.amdhsa_accum_offset 256
		.amdhsa_reserve_vcc 1
		.amdhsa_float_round_mode_32 0
		.amdhsa_float_round_mode_16_64 0
		.amdhsa_float_denorm_mode_32 3
		.amdhsa_float_denorm_mode_16_64 3
		.amdhsa_dx10_clamp 1
		.amdhsa_ieee_mode 1
		.amdhsa_fp16_overflow 0
		.amdhsa_tg_split 0
		.amdhsa_exception_fp_ieee_invalid_op 0
		.amdhsa_exception_fp_denorm_src 0
		.amdhsa_exception_fp_ieee_div_zero 0
		.amdhsa_exception_fp_ieee_overflow 0
		.amdhsa_exception_fp_ieee_underflow 0
		.amdhsa_exception_fp_ieee_inexact 0
		.amdhsa_exception_int_div_zero 0
	.end_amdhsa_kernel

; __global__ void __launch_bounds__(NTHR, 2) mk_fwd(Args args) {
amdhsa.kernels:
  - .agpr_count:     0
    .args:
      - .offset:         0
        .size:           160
        .value_kind:     by_value
      - .offset:         160
        .size:           4
        .value_kind:     hidden_block_count_x
      - .offset:         164
        .size:           4
        .value_kind:     hidden_block_count_y
      - .offset:         168
        .size:           4
        .value_kind:     hidden_block_count_z
      - .offset:         172
        .size:           2
        .value_kind:     hidden_group_size_x
      - .offset:         174
        .size:           2
        .value_kind:     hidden_group_size_y
      - .offset:         176
        .size:           2
        .value_kind:     hidden_group_size_z
      - .offset:         178
        .size:           2
        .value_kind:     hidden_remainder_x
      - .offset:         180
        .size:           2
        .value_kind:     hidden_remainder_y
      - .offset:         182
        .size:           2
        .value_kind:     hidden_remainder_z
      - .offset:         200
        .size:           8
        .value_kind:     hidden_global_offset_x
      - .offset:         208
        .size:           8
        .value_kind:     hidden_global_offset_y
      - .offset:         216
        .size:           8
        .value_kind:     hidden_global_offset_z
      - .offset:         224
        .size:           2
        .value_kind:     hidden_grid_dims
      - .offset:         280
        .size:           4
        .value_kind:     hidden_dynamic_lds_size
    .group_segment_fixed_size: 0
    .kernarg_segment_align: 8
    .kernarg_segment_size: 416
    .language:       OpenCL C
    .language_version:
      - 2
      - 0
    .max_flat_workgroup_size: 512
    .name:           _Z6mk_fwd4Args
    .private_segment_fixed_size: 0
    .sgpr_count:     108
    .sgpr_spill_count: 53
    .symbol:         _Z6mk_fwd4Args.kd
    .uniform_work_group_size: 1
    .uses_dynamic_stack: false
    .vgpr_count:     256
    .vgpr_spill_count: 0
    .wavefront_size: 64
